# attention: next-item atomic no longer waited at issue (wait deferred to slot publish), plus vmcnt-free QK waits in MoBA/SWA, plus softmax edits
# baseline (speedup 1.0000x reference)
; template <int DQ, int TYPE>
; __device__ __forceinline__ void attn_item(PP p, int layer, int b, int h, int qt, char* lds, const int tid_, unsigned* next_ctr, volatile XLAS unsigned* slot) {
;     ...
;         if (!skip) {
;             const bf16_t* Ks = (const bf16_t*)(lds + buf * STAGE); const bf16_t* Vt = (const bf16_t*)(lds + buf * STAGE + KBYTES);
;             f32x16 sacc;
; #pragma unroll
;             for (int i = 0; i < 16; ++i) sacc[i] = 0.f;
;             const bf16_t* kb_ = Ks + (32 * kh + r) * KLD + 8 * hh;
;             bf16x8 kf[2][GK];
; #pragma unroll
;             for (int i = 0; i < GK; ++i) kf[0][i] = *(const bf16x8*)(kb_ + 16 * i);
; #pragma unroll
;             for (int g = 0; g < NG; ++g) {
;                 if (g + 1 < NG) {
; #pragma unroll
;                     for (int i = 0; i < GK; ++i) kf[(g + 1) & 1][i] = *(const bf16x8*)(kb_ + 16 * ((g + 1) * GK + i));
;                 }
;                 __builtin_amdgcn_sched_barrier(0);
; #pragma unroll
;                 for (int i = 0; i < GK; ++i) sacc = __builtin_amdgcn_mfma_f32_32x32x16_bf16(kf[g & 1][i], qf[g * GK + i], sacc, 0, 0, 0);
;                 __builtin_amdgcn_sched_barrier(0);
;             }
;             const bf16_t* vb0 = Vt + r * VLD + 32 * kh + 4 * hh;
;             u32x2 vf[2][4][2];
; #pragma unroll
;             for (int md = 0; md < 4; ++md) { vf[0][md][0] = *(const u32x2*)(vb0 + md * 32 * VLD); vf[0][md][1] = *(const u32x2*)(vb0 + md * 32 * VLD + 8); }
;             if (mode != 0) {
;                 const bool selbit = (qmask >> (j >> 2)) & 1u;
; #pragma unroll
;                 for (int i = 0; i < 16; ++i) {
;                     const int kpos = kbase_pos + 8 * (i >> 2) + 4 * hh + (i & 3);
;                     const int dd = qpos - kpos;
;                     bool ok;
;                     if (mode == 1) ok = dd >= 0; else if (mode == 2) ok = (dd >= 0 && dd < 128); else ok = selbit;
;                     if (!ok) sacc[i] = -INFINITY;
;                 }
;             }
;             float mx = fmaxf(sacc[0], sacc[1]);
; #pragma unroll
;             for (int i = 2; i < 16; i += 2) mx = fmaxf(mx, fmaxf(sacc[i], sacc[i + 1]));
;             mx *= c;
;             mx = fmaxf(mx, __shfl_xor(mx, 32));
;             const float m_old_ = m_run;
;             const float mnew = fmaxf(m_run, mx);
;             const float alpha = fast_exp2(m_run - mnew);
.LBB0_408:
	s_and_b32 s60, s12, 1
	s_cmp_gt_i32 s59, s57
	s_cselect_b64 s[62:63], -1, 0
	s_add_i32 s61, s59, 31
	s_cmp_le_i32 s61, s58
	s_cselect_b64 s[64:65], -1, 0
	s_or_b64 s[62:63], s[64:65], s[62:63]
	s_and_b64 vcc, exec, s[62:63]
	s_cbranch_vccnz .LBB0_412
	s_mul_i32 s61, s60, 0x8800
	s_add_i32 s61, s61, 16
	v_add3_u32 v0, s61, v163, v167
	ds_read_b128 v[2:5], v0
	ds_read_b128 v[6:9], v0 offset:32
	ds_read_b128 v[10:13], v0 offset:64
	ds_read_b128 v[170:173], v0 offset:96
	ds_read_b128 v[174:177], v0 offset:128
	ds_read_b128 v[190:193], v0 offset:160
	ds_read_b128 v[194:197], v0 offset:192
	ds_read_b128 v[198:201], v0 offset:224
	s_waitcnt lgkmcnt(7)
	v_mfma_f32_32x32x16_bf16 v[80:95], v[2:5], v[104:107], 0
	s_waitcnt lgkmcnt(6)
	v_mfma_f32_32x32x16_bf16 v[80:95], v[6:9], v[108:111], v[80:95]
	s_waitcnt lgkmcnt(5)
	v_mfma_f32_32x32x16_bf16 v[80:95], v[10:13], v[112:115], v[80:95]
	s_waitcnt lgkmcnt(4)
	v_mfma_f32_32x32x16_bf16 v[80:95], v[170:173], v[120:123], v[80:95]
	s_waitcnt lgkmcnt(3)
	v_mfma_f32_32x32x16_bf16 v[80:95], v[174:177], v[124:127], v[80:95]
	s_lshl_b32 s62, s13, 1
	v_add_u32_e32 v10, 27, v165
	s_add_i32 s62, s62, s61
	v_cmp_gt_u32_e32 vcc, s42, v10
	s_movk_i32 s61, 0xff7f
	v_add_u32_e32 v11, 25, v165
	v_add_u32_e32 v12, 24, v165
	s_waitcnt lgkmcnt(2)
	v_mfma_f32_32x32x16_bf16 v[80:95], v[190:193], v[132:135], v[80:95]
	v_add_u32_e32 v13, 19, v165
	v_add_u32_e32 v14, 18, v165
	v_add_u32_e32 v175, 17, v165
	v_add_u32_e32 v176, 16, v165
	v_add_u32_e32 v10, 11, v165
	v_lshlrev_b32_e32 v0, 1, v155
	v_add3_u32 v0, s62, v164, v0
	s_waitcnt lgkmcnt(1)
	v_mfma_f32_32x32x16_bf16 v[80:95], v[194:197], v[136:139], v[80:95]
	v_add_u32_e32 v169, 0x4000, v0
	v_add_u32_e32 v15, 0x5000, v0
	ds_read2_b64 v[2:5], v169 offset0:128 offset1:130
	ds_read2_b64 v[6:9], v15 offset0:160 offset1:162
	s_waitcnt lgkmcnt(2)
	v_mfma_f32_32x32x16_bf16 v[80:95], v[198:201], v[140:143], v[80:95]
	s_nop 11
	v_cndmask_b32_e32 v170, v225, v80, vcc
	v_cmp_lt_u32_e32 vcc, s61, v166
	s_nop 1
	v_cndmask_b32_e32 v172, v225, v81, vcc
	v_cmp_gt_u32_e32 vcc, s42, v11
	s_nop 1
	v_cndmask_b32_e32 v173, v225, v82, vcc
	v_cmp_gt_u32_e32 vcc, s42, v12
	v_max_f32_e32 v11, v173, v173
	s_nop 0
	v_cndmask_b32_e32 v174, v225, v83, vcc
	v_cmp_gt_u32_e32 vcc, s42, v13
	s_nop 1
	v_cndmask_b32_e32 v171, v225, v84, vcc
	v_cmp_gt_u32_e32 vcc, s42, v14
	v_max_f32_e32 v12, v171, v171
	s_nop 0
	v_cndmask_b32_e32 v85, v225, v85, vcc
	v_cmp_gt_u32_e32 vcc, s42, v175
	s_nop 1
	v_cndmask_b32_e32 v177, v225, v86, vcc
	v_cmp_gt_u32_e32 vcc, s42, v176
	v_max_f32_e32 v13, v177, v177
	s_nop 0
	v_cndmask_b32_e32 v176, v225, v87, vcc
	v_cmp_gt_u32_e32 vcc, s42, v10
	v_add_u32_e32 v10, 10, v165
	s_nop 0
	v_cndmask_b32_e32 v175, v225, v88, vcc
	v_cmp_gt_u32_e32 vcc, s42, v10
	v_add_u32_e32 v10, 9, v165
	s_nop 0
	v_cndmask_b32_e32 v89, v225, v89, vcc
	v_cmp_gt_u32_e32 vcc, s42, v10
	v_add_u32_e32 v10, 8, v165
	s_nop 0
	v_cndmask_b32_e32 v90, v225, v90, vcc
	v_cmp_gt_u32_e32 vcc, s42, v10
	v_add_u32_e32 v10, 3, v165
	s_nop 0
	v_cndmask_b32_e32 v91, v225, v91, vcc
	v_cmp_gt_u32_e32 vcc, s42, v10
	v_add_u32_e32 v10, 2, v165
	s_nop 0
	v_cndmask_b32_e32 v86, v225, v92, vcc
	v_cmp_gt_u32_e32 vcc, s42, v10
	v_add_u32_e32 v10, 1, v165
	v_add_u32_e32 v92, 0x7000, v0
	v_cndmask_b32_e32 v87, v225, v93, vcc
	v_cmp_gt_u32_e32 vcc, s42, v10
	v_max_f32_e32 v10, v174, v174
	v_max_f32_e32 v10, v11, v10
	v_max_f32_e32 v11, v85, v85
	v_max_f32_e32 v11, v12, v11
	v_max_f32_e32 v12, v176, v176
	v_max3_f32 v10, v170, v172, v10
	v_max_f32_e32 v12, v13, v12
	v_max3_f32 v10, v10, v11, v12
	v_max_f32_e32 v11, v89, v89
	v_max_f32_e32 v12, v175, v175
	v_max_f32_e32 v11, v12, v11
	v_max_f32_e32 v12, v91, v91
	v_max_f32_e32 v13, v90, v90
	v_cndmask_b32_e32 v88, v225, v94, vcc
	v_cmp_gt_u32_e32 vcc, s42, v165
	v_max_f32_e32 v12, v13, v12
	v_max3_f32 v10, v10, v11, v12
	v_cndmask_b32_e32 v84, v225, v95, vcc
	v_max_f32_e32 v11, v87, v87
	v_max_f32_e32 v12, v86, v86
	v_max_f32_e32 v11, v12, v11
	v_max_f32_e32 v12, v84, v84
	v_max_f32_e32 v13, v88, v88
	v_max_f32_e32 v12, v13, v12
	v_max3_f32 v10, v10, v11, v12
	v_mul_f32_e32 v14, 0x3e0293ee, v10
	v_add_u32_e32 v93, 0x6000, v0
	ds_read2_b64 v[80:83], v93 offset0:192 offset1:194
	v_mov_b32_e32 v94, v14
	ds_read2_b64 v[10:13], v92 offset0:224 offset1:226
	s_nop 1
	v_permlane32_swap_b32_e32 v94, v14
	v_max_f32_e32 v94, v14, v94
	v_add_f32_e32 v0, 0x41000000, v168
	v_cmp_gt_f32_e32 vcc, v94, v0
	s_nop 1
	v_cndmask_b32_e32 v14, v168, v94, vcc
	v_sub_f32_e32 v0, v168, v14
	v_exp_f32_e32 v0, v0
	s_cbranch_vccz .LBB0_411
	v_pk_mul_f32 v[46:47], v[46:47], v[0:1] op_sel_hi:[1,0]
	v_pk_mul_f32 v[44:45], v[44:45], v[0:1] op_sel_hi:[1,0]
	v_pk_mul_f32 v[42:43], v[42:43], v[0:1] op_sel_hi:[1,0]
	v_pk_mul_f32 v[40:41], v[40:41], v[0:1] op_sel_hi:[1,0]
	v_pk_mul_f32 v[38:39], v[38:39], v[0:1] op_sel_hi:[1,0]
	v_pk_mul_f32 v[36:37], v[36:37], v[0:1] op_sel_hi:[1,0]
	v_pk_mul_f32 v[34:35], v[34:35], v[0:1] op_sel_hi:[1,0]
	v_pk_mul_f32 v[32:33], v[32:33], v[0:1] op_sel_hi:[1,0]
	v_pk_mul_f32 v[30:31], v[30:31], v[0:1] op_sel_hi:[1,0]
	v_pk_mul_f32 v[28:29], v[28:29], v[0:1] op_sel_hi:[1,0]
	v_pk_mul_f32 v[26:27], v[26:27], v[0:1] op_sel_hi:[1,0]
	v_pk_mul_f32 v[24:25], v[24:25], v[0:1] op_sel_hi:[1,0]
	v_pk_mul_f32 v[22:23], v[22:23], v[0:1] op_sel_hi:[1,0]
	v_pk_mul_f32 v[20:21], v[20:21], v[0:1] op_sel_hi:[1,0]
	v_pk_mul_f32 v[18:19], v[18:19], v[0:1] op_sel_hi:[1,0]
	v_pk_mul_f32 v[16:17], v[16:17], v[0:1] op_sel_hi:[1,0]
	v_pk_mul_f32 v[78:79], v[78:79], v[0:1] op_sel_hi:[1,0]
	v_pk_mul_f32 v[76:77], v[76:77], v[0:1] op_sel_hi:[1,0]
	v_pk_mul_f32 v[74:75], v[74:75], v[0:1] op_sel_hi:[1,0]
	v_pk_mul_f32 v[72:73], v[72:73], v[0:1] op_sel_hi:[1,0]
	v_pk_mul_f32 v[70:71], v[70:71], v[0:1] op_sel_hi:[1,0]
	v_pk_mul_f32 v[68:69], v[68:69], v[0:1] op_sel_hi:[1,0]
	v_pk_mul_f32 v[66:67], v[66:67], v[0:1] op_sel_hi:[1,0]
	v_pk_mul_f32 v[64:65], v[64:65], v[0:1] op_sel_hi:[1,0]
	v_pk_mul_f32 v[62:63], v[62:63], v[0:1] op_sel_hi:[1,0]
	v_pk_mul_f32 v[60:61], v[60:61], v[0:1] op_sel_hi:[1,0]
	v_pk_mul_f32 v[58:59], v[58:59], v[0:1] op_sel_hi:[1,0]
	v_pk_mul_f32 v[56:57], v[56:57], v[0:1] op_sel_hi:[1,0]
	v_pk_mul_f32 v[54:55], v[54:55], v[0:1] op_sel_hi:[1,0]
	v_pk_mul_f32 v[52:53], v[52:53], v[0:1] op_sel_hi:[1,0]
	v_pk_mul_f32 v[50:51], v[50:51], v[0:1] op_sel_hi:[1,0]
	v_pk_mul_f32 v[48:49], v[48:49], v[0:1] op_sel_hi:[1,0]

; template <int DQ, int TYPE>
; __device__ __forceinline__ void attn_item(PP p, int layer, int b, int h, int qt, char* lds, const int tid_, unsigned* next_ctr, volatile XLAS unsigned* slot) {
;     ...
;     __builtin_amdgcn_s_setprio(0);
;     unsigned nxt_item = 0; if (tid_ == 0) nxt_item = atomicAdd(next_ctr, 1u);
;     l_run += __shfl_xor(l_run, 32);
;     float* mrg = (float*)lds;
;     {
;         float* mp = mrg + (size_t)((qg * 2 + kh) * 34) * 64 + lane;
;         if (kh == 0) {
; #pragma unroll
;             for (int t2 = 0; t2 < 2; ++t2)
; #pragma unroll
;                 for (int i = 0; i < 16; ++i) mp[(t2 * 16 + i) * 64] = O[2 + t2][i];
;         } else {
; #pragma unroll
;             for (int t2 = 0; t2 < 2; ++t2)
; #pragma unroll
;                 for (int i = 0; i < 16; ++i) mp[(t2 * 16 + i) * 64] = O[t2][i];
;         }
;         mp[32 * 64] = m_run; mp[33 * 64] = l_run;
;     }
;     __syncthreads();
.LBB0_414:
	s_lshl_b32 s57, s50, 7
	s_setprio 0
	v_mov_b32_e32 v10, 0
	v_cmp_eq_u32_e64 s[50:51], 0, v181
	s_and_saveexec_b64 s[12:13], s[50:51]
	s_cbranch_execz .LBB0_418
	s_mov_b64 s[16:17], exec
	v_mbcnt_lo_u32_b32 v0, s16, 0
	v_mbcnt_hi_u32_b32 v0, s17, v0
	v_cmp_eq_u32_e32 vcc, 0, v0
	s_and_saveexec_b64 s[14:15], vcc
	s_cbranch_execz .LBB0_417
	s_bcnt1_i32_b64 s16, s[16:17]
	s_lshl_b32 s17, s47, 2
	v_mov_b32_e32 v2, s17
	v_mov_b32_e32 v3, s16
	global_atomic_add v250, v2, v3, s[6:7] sc0
.LBB0_417:
	s_or_b64 exec, exec, s[14:15]
.LBB0_418:
	s_or_b64 exec, exec, s[12:13]
	s_load_dwordx2 s[14:15], s[0:1], 0x98
	s_lshl_b32 s12, s55, 12
	v_and_b32_e32 v2, 64, v224
	v_xor_b32_e32 v0, 32, v224
	v_add_u32_e32 v2, 64, v2
	s_waitcnt lgkmcnt(0)
	s_add_u32 s12, s14, s12
	s_addc_u32 s13, s15, 0
	s_lshl_b32 s14, s57, 1
	s_add_u32 s12, s12, s14
	v_cmp_lt_i32_e32 vcc, v0, v2
	s_addc_u32 s13, s13, 0
	s_lshl_b32 s14, s49, 1
	v_cndmask_b32_e32 v0, v224, v0, vcc
	s_add_i32 s15, s14, s56
	v_lshlrev_b32_e32 v0, 2, v0
	s_mulk_i32 s15, 0x2200
	ds_bpermute_b32 v0, v0, v158
	s_add_i32 s15, s15, 16
	v_lshlrev_b32_e32 v2, 2, v156
	v_add_u32_e32 v3, s15, v2
	s_xor_b32 s15, s56, 1
	s_add_i32 s14, s14, s15
	s_mulk_i32 s14, 0x2200
	v_cndmask_b32_e64 v12, v40, v72, s[52:53]
	v_cndmask_b32_e64 v83, v33, v65, s[52:53]
	v_cndmask_b32_e64 v84, v32, v64, s[52:53]
	s_add_i32 s14, s14, 16
	s_waitcnt lgkmcnt(0)
	v_add_f32_e32 v0, v158, v0
	v_cndmask_b32_e64 v4, v47, v79, s[52:53]
	v_cndmask_b32_e64 v5, v46, v78, s[52:53]
	v_cndmask_b32_e64 v6, v45, v77, s[52:53]
	v_cndmask_b32_e64 v7, v44, v76, s[52:53]
	v_cndmask_b32_e64 v8, v43, v75, s[52:53]
	v_cndmask_b32_e64 v9, v42, v74, s[52:53]
	v_cndmask_b32_e64 v11, v41, v73, s[52:53]
	v_cndmask_b32_e64 v13, v39, v71, s[52:53]
	v_cndmask_b32_e64 v14, v38, v70, s[52:53]
	v_cndmask_b32_e64 v15, v37, v69, s[52:53]
	v_cndmask_b32_e64 v80, v36, v68, s[52:53]
	v_cndmask_b32_e64 v81, v35, v67, s[52:53]
	v_cndmask_b32_e64 v82, v34, v66, s[52:53]
	v_cndmask_b32_e64 v85, v31, v63, s[52:53]
	v_cndmask_b32_e64 v86, v30, v62, s[52:53]
	v_cndmask_b32_e64 v87, v29, v61, s[52:53]
	v_cndmask_b32_e64 v88, v28, v60, s[52:53]
	v_cndmask_b32_e64 v89, v27, v59, s[52:53]
	v_cndmask_b32_e64 v90, v26, v58, s[52:53]
	v_cndmask_b32_e64 v91, v25, v57, s[52:53]
	v_cndmask_b32_e64 v92, v24, v56, s[52:53]
	v_cndmask_b32_e64 v93, v23, v55, s[52:53]
	v_cndmask_b32_e64 v94, v22, v54, s[52:53]
	v_cndmask_b32_e64 v95, v21, v53, s[52:53]
	s_waitcnt vmcnt(3)
	v_cndmask_b32_e64 v96, v20, v52, s[52:53]
	v_cndmask_b32_e64 v97, v19, v51, s[52:53]
	v_cndmask_b32_e64 v98, v18, v50, s[52:53]
	v_cndmask_b32_e64 v99, v17, v49, s[52:53]
	s_waitcnt vmcnt(2)
	v_cndmask_b32_e64 v100, v16, v48, s[52:53]
	ds_write2st64_b32 v3, v84, v83 offset1:1
	ds_write2st64_b32 v3, v82, v81 offset0:2 offset1:3
	ds_write2st64_b32 v3, v80, v15 offset0:4 offset1:5
	ds_write2st64_b32 v3, v14, v13 offset0:6 offset1:7
	ds_write2st64_b32 v3, v12, v11 offset0:8 offset1:9
	ds_write2st64_b32 v3, v9, v8 offset0:10 offset1:11
	ds_write2st64_b32 v3, v7, v6 offset0:12 offset1:13
	ds_write2st64_b32 v3, v5, v4 offset0:14 offset1:15
	ds_write2st64_b32 v3, v100, v99 offset0:16 offset1:17
	ds_write2st64_b32 v3, v98, v97 offset0:18 offset1:19
	ds_write2st64_b32 v3, v96, v95 offset0:20 offset1:21
	ds_write2st64_b32 v3, v94, v93 offset0:22 offset1:23
	ds_write2st64_b32 v3, v92, v91 offset0:24 offset1:25
	ds_write2st64_b32 v3, v90, v89 offset0:26 offset1:27
	ds_write2st64_b32 v3, v88, v87 offset0:28 offset1:29
	ds_write2st64_b32 v3, v86, v85 offset0:30 offset1:31
	ds_write2st64_b32 v3, v168, v0 offset0:32 offset1:33
	v_add_u32_e32 v12, s14, v2
	s_waitcnt lgkmcnt(0)
	s_barrier
	ds_read2st64_b32 v[4:5], v12 offset0:32 offset1:33
	v_max_f32_e32 v3, v168, v168
	s_waitcnt lgkmcnt(0)
	v_max_f32_e32 v2, v4, v4
	v_max_f32_e32 v2, v3, v2
	v_sub_f32_e32 v6, v168, v2
	v_sub_f32_e32 v2, v4, v2
	v_exp_f32_e32 v3, v2
	v_exp_f32_e32 v4, v6
	v_mul_f32_e32 v2, v5, v3
	v_fmac_f32_e32 v2, v0, v4
	v_div_scale_f32 v0, s[14:15], v2, v2, 1.0
	v_rcp_f32_e32 v5, v0
	s_nop 0
	v_fma_f32 v6, -v0, v5, 1.0
	v_fmac_f32_e32 v5, v6, v5
	v_div_scale_f32 v6, vcc, 1.0, v2, 1.0
	v_mul_f32_e32 v7, v6, v5
	v_fma_f32 v8, -v0, v7, v6
	v_fmac_f32_e32 v7, v8, v5
	v_fma_f32 v0, -v0, v7, v6
	v_div_fmas_f32 v0, v0, v5, v7
	v_div_fixup_f32 v11, v0, v2, 1.0
	v_lshlrev_b32_e32 v0, 12, v154
	v_lshl_add_u64 v[6:7], s[12:13], 0, v[0:1]
	s_mov_b64 s[12:13], 0x27388800
	v_lshl_add_u64 v[6:7], v[6:7], 0, s[12:13]
	s_mov_b64 s[12:13], -1
	s_andn2_b64 vcc, exec, s[8:9]
	v_lshlrev_b32_e32 v0, 1, v155
	s_cbranch_vccnz .LBB0_680
; __device__ __forceinline__ float fast_exp2(float x) { return __builtin_amdgcn_exp2f(x); }
; template <int DQ, int TYPE>
; __device__ __forceinline__ void attn_item(PP p, int layer, int b, int h, int qt, char* lds, const int tid_, unsigned* next_ctr, volatile XLAS unsigned* slot) {
;     ...
;     {
;         const float* mp = mrg + (size_t)((qg * 2 + (kh ^ 1)) * 34) * 64 + lane;
;         const float m1 = mp[32 * 64], l1 = mp[33 * 64];
;         const float mt = fmaxf(m_run, m1);
;         const float a0 = fast_exp2(m_run - mt), a1 = fast_exp2(m1 - mt);
;         const float inv = 1.0f / (l_run * a0 + l1 * a1);
;         bf16_t* orow = Op + (size_t)qpos * D;
;     ...
;         if (kh == 0) A_MERGE(0); else A_MERGE(2);
	ds_read2st64_b32 v[14:15], v12 offset1:1
	v_mov_b32_e32 v2, v64
	v_lshl_add_u64 v[8:9], v[6:7], 0, v[0:1]
	s_waitcnt lgkmcnt(0)
	v_mov_b32_e32 v5, v14
	v_pk_mul_f32 v[80:81], v[2:3], v[4:5]
	v_mov_b32_e32 v5, v15
	v_add_f32_e32 v2, v80, v81
	v_mul_f32_e32 v13, v11, v2
	v_mov_b32_e32 v2, v65
	v_pk_mul_f32 v[14:15], v[2:3], v[4:5]
	s_nop 0
	v_add_f32_e32 v2, v14, v15
	ds_read2st64_b32 v[14:15], v12 offset0:2 offset1:3
	v_mul_f32_e32 v80, v11, v2
	v_mov_b32_e32 v2, v66
	s_waitcnt lgkmcnt(0)
	v_mov_b32_e32 v5, v14
	v_pk_mul_f32 v[64:65], v[2:3], v[4:5]
	v_mov_b32_e32 v5, v15
	v_add_f32_e32 v2, v64, v65
	v_mul_f32_e32 v64, v11, v2
	v_mov_b32_e32 v2, v67
	v_pk_mul_f32 v[14:15], v[2:3], v[4:5]
	s_nop 0
	v_add_f32_e32 v2, v14, v15
	v_mul_f32_e32 v2, v11, v2
	v_cvt_pk_bf16_f32 v14, v13, v80
	v_cvt_pk_bf16_f32 v15, v64, v2
	global_store_dwordx2 v[8:9], v[14:15], off offset:128
	ds_read2st64_b32 v[14:15], v12 offset0:4 offset1:5
	v_mov_b32_e32 v2, v68
	s_waitcnt lgkmcnt(0)
	v_mov_b32_e32 v5, v14
	v_pk_mul_f32 v[64:65], v[2:3], v[4:5]
	v_mov_b32_e32 v5, v15
	v_add_f32_e32 v2, v64, v65
	v_mul_f32_e32 v13, v11, v2
	v_mov_b32_e32 v2, v69
	v_pk_mul_f32 v[14:15], v[2:3], v[4:5]
	s_nop 0
	v_add_f32_e32 v2, v14, v15
	ds_read2st64_b32 v[14:15], v12 offset0:6 offset1:7
	v_mul_f32_e32 v66, v11, v2
	v_mov_b32_e32 v2, v70
	s_waitcnt lgkmcnt(0)
	v_mov_b32_e32 v5, v14
	v_pk_mul_f32 v[64:65], v[2:3], v[4:5]
	v_mov_b32_e32 v5, v15
	v_add_f32_e32 v2, v64, v65
	v_mul_f32_e32 v64, v11, v2
	v_mov_b32_e32 v2, v71
	v_pk_mul_f32 v[14:15], v[2:3], v[4:5]
	s_nop 0
	v_add_f32_e32 v2, v14, v15
	v_mul_f32_e32 v2, v11, v2
	v_cvt_pk_bf16_f32 v14, v13, v66
	v_cvt_pk_bf16_f32 v15, v64, v2
	global_store_dwordx2 v[8:9], v[14:15], off offset:144
	ds_read2st64_b32 v[14:15], v12 offset0:8 offset1:9
	v_mov_b32_e32 v2, v72
	s_waitcnt lgkmcnt(0)
	v_mov_b32_e32 v5, v14
	v_pk_mul_f32 v[64:65], v[2:3], v[4:5]
	v_mov_b32_e32 v5, v15
	v_add_f32_e32 v2, v64, v65
	v_mul_f32_e32 v13, v11, v2
	v_mov_b32_e32 v2, v73
	v_pk_mul_f32 v[14:15], v[2:3], v[4:5]
	s_nop 0
	v_add_f32_e32 v2, v14, v15
	ds_read2st64_b32 v[14:15], v12 offset0:10 offset1:11
	v_mul_f32_e32 v66, v11, v2
	v_mov_b32_e32 v2, v74
	s_waitcnt lgkmcnt(0)
	v_mov_b32_e32 v5, v14
	v_pk_mul_f32 v[64:65], v[2:3], v[4:5]
	v_mov_b32_e32 v5, v15
	v_add_f32_e32 v2, v64, v65
	v_mul_f32_e32 v64, v11, v2
	v_mov_b32_e32 v2, v75
	v_pk_mul_f32 v[14:15], v[2:3], v[4:5]
	s_nop 0
	v_add_f32_e32 v2, v14, v15
	v_mul_f32_e32 v2, v11, v2
	v_cvt_pk_bf16_f32 v14, v13, v66
	v_cvt_pk_bf16_f32 v15, v64, v2
	global_store_dwordx2 v[8:9], v[14:15], off offset:160
	ds_read2st64_b32 v[14:15], v12 offset0:12 offset1:13
	v_mov_b32_e32 v2, v76
	s_waitcnt lgkmcnt(0)
	v_mov_b32_e32 v5, v14
	v_pk_mul_f32 v[64:65], v[2:3], v[4:5]
	v_mov_b32_e32 v5, v15
	v_add_f32_e32 v2, v64, v65
	v_mul_f32_e32 v13, v11, v2
	v_mov_b32_e32 v2, v77
	v_pk_mul_f32 v[14:15], v[2:3], v[4:5]
	s_nop 0
	v_add_f32_e32 v2, v14, v15
	ds_read2st64_b32 v[14:15], v12 offset0:14 offset1:15
	v_mul_f32_e32 v66, v11, v2
	v_mov_b32_e32 v2, v78
	s_waitcnt lgkmcnt(0)
	v_mov_b32_e32 v5, v14
	v_pk_mul_f32 v[64:65], v[2:3], v[4:5]
	v_mov_b32_e32 v5, v15
	v_add_f32_e32 v2, v64, v65
	v_mul_f32_e32 v64, v11, v2
	v_mov_b32_e32 v2, v79
	v_pk_mul_f32 v[14:15], v[2:3], v[4:5]
	s_nop 0
	v_add_f32_e32 v2, v14, v15
	v_mul_f32_e32 v2, v11, v2
	v_cvt_pk_bf16_f32 v14, v13, v66
	v_cvt_pk_bf16_f32 v15, v64, v2
	global_store_dwordx2 v[8:9], v[14:15], off offset:176
	ds_read2st64_b32 v[14:15], v12 offset0:16 offset1:17
	v_mov_b32_e32 v2, v48
	s_waitcnt lgkmcnt(0)
	v_mov_b32_e32 v5, v14
	v_pk_mul_f32 v[64:65], v[2:3], v[4:5]
	v_mov_b32_e32 v5, v15
	v_add_f32_e32 v2, v64, v65
	v_mul_f32_e32 v13, v11, v2
	v_mov_b32_e32 v2, v49
	v_pk_mul_f32 v[14:15], v[2:3], v[4:5]
	s_nop 0
	v_add_f32_e32 v2, v14, v15
	ds_read2st64_b32 v[14:15], v12 offset0:18 offset1:19
	v_mul_f32_e32 v64, v11, v2
	v_mov_b32_e32 v2, v50
	s_waitcnt lgkmcnt(0)
	v_mov_b32_e32 v5, v14
	v_pk_mul_f32 v[48:49], v[2:3], v[4:5]
	v_mov_b32_e32 v5, v15
	v_add_f32_e32 v2, v48, v49
	v_mul_f32_e32 v48, v11, v2
	v_mov_b32_e32 v2, v51
	v_pk_mul_f32 v[14:15], v[2:3], v[4:5]
	s_nop 0
	v_add_f32_e32 v2, v14, v15
	v_mul_f32_e32 v2, v11, v2
	v_cvt_pk_bf16_f32 v14, v13, v64
	v_cvt_pk_bf16_f32 v15, v48, v2
	global_store_dwordx2 v[8:9], v[14:15], off offset:192
	ds_read2st64_b32 v[14:15], v12 offset0:20 offset1:21
	v_mov_b32_e32 v2, v52
	s_waitcnt lgkmcnt(0)
	v_mov_b32_e32 v5, v14
	v_pk_mul_f32 v[48:49], v[2:3], v[4:5]
	v_mov_b32_e32 v5, v15
	v_add_f32_e32 v2, v48, v49
	v_mul_f32_e32 v13, v11, v2
	v_mov_b32_e32 v2, v53
	v_pk_mul_f32 v[14:15], v[2:3], v[4:5]
	s_nop 0
	v_add_f32_e32 v2, v14, v15
	ds_read2st64_b32 v[14:15], v12 offset0:22 offset1:23
	v_mul_f32_e32 v50, v11, v2
	v_mov_b32_e32 v2, v54
	s_waitcnt lgkmcnt(0)
	v_mov_b32_e32 v5, v14
	v_pk_mul_f32 v[48:49], v[2:3], v[4:5]
	v_mov_b32_e32 v5, v15
	v_add_f32_e32 v2, v48, v49
	v_mul_f32_e32 v48, v11, v2
	v_mov_b32_e32 v2, v55
	v_pk_mul_f32 v[14:15], v[2:3], v[4:5]
	s_nop 0
	v_add_f32_e32 v2, v14, v15
	v_mul_f32_e32 v2, v11, v2
	v_cvt_pk_bf16_f32 v14, v13, v50
	v_cvt_pk_bf16_f32 v15, v48, v2
	global_store_dwordx2 v[8:9], v[14:15], off offset:208
	ds_read2st64_b32 v[14:15], v12 offset0:24 offset1:25
	v_mov_b32_e32 v2, v56
	s_waitcnt lgkmcnt(0)
	v_mov_b32_e32 v5, v14
	v_pk_mul_f32 v[48:49], v[2:3], v[4:5]
	v_mov_b32_e32 v5, v15
	v_add_f32_e32 v2, v48, v49
	v_mul_f32_e32 v13, v11, v2
	v_mov_b32_e32 v2, v57
	v_pk_mul_f32 v[14:15], v[2:3], v[4:5]
	s_nop 0
	v_add_f32_e32 v2, v14, v15
	ds_read2st64_b32 v[14:15], v12 offset0:26 offset1:27
	v_mul_f32_e32 v50, v11, v2
	v_mov_b32_e32 v2, v58
	s_waitcnt lgkmcnt(0)
	v_mov_b32_e32 v5, v14
	v_pk_mul_f32 v[48:49], v[2:3], v[4:5]
	v_mov_b32_e32 v5, v15
	v_add_f32_e32 v2, v48, v49
	v_mul_f32_e32 v48, v11, v2
	v_mov_b32_e32 v2, v59
	v_pk_mul_f32 v[14:15], v[2:3], v[4:5]
	s_nop 0
	v_add_f32_e32 v2, v14, v15
	v_mul_f32_e32 v2, v11, v2
	v_cvt_pk_bf16_f32 v14, v13, v50
	v_cvt_pk_bf16_f32 v15, v48, v2
	global_store_dwordx2 v[8:9], v[14:15], off offset:224
	ds_read2st64_b32 v[14:15], v12 offset0:28 offset1:29
	v_mov_b32_e32 v2, v60
	s_waitcnt lgkmcnt(0)
	v_mov_b32_e32 v5, v14
	v_pk_mul_f32 v[48:49], v[2:3], v[4:5]
	v_mov_b32_e32 v5, v15
	v_add_f32_e32 v2, v48, v49
	v_mul_f32_e32 v13, v11, v2
	v_mov_b32_e32 v2, v61
	v_pk_mul_f32 v[14:15], v[2:3], v[4:5]
	s_nop 0
	v_add_f32_e32 v2, v14, v15
	ds_read2st64_b32 v[14:15], v12 offset0:30 offset1:31
	v_mul_f32_e32 v50, v11, v2
	v_mov_b32_e32 v2, v62
	s_waitcnt lgkmcnt(0)
	v_mov_b32_e32 v5, v14
	v_pk_mul_f32 v[48:49], v[2:3], v[4:5]
	v_mov_b32_e32 v5, v15
	v_add_f32_e32 v2, v48, v49
	v_mul_f32_e32 v48, v11, v2
	v_mov_b32_e32 v2, v63
	v_pk_mul_f32 v[14:15], v[2:3], v[4:5]
	s_nop 0
	v_add_f32_e32 v2, v14, v15
	v_mul_f32_e32 v2, v11, v2
	v_cvt_pk_bf16_f32 v14, v13, v50
	v_cvt_pk_bf16_f32 v15, v48, v2
	global_store_dwordx2 v[8:9], v[14:15], off offset:240
	s_cbranch_execz .LBB0_681

; template <int DQ, int TYPE>
; __device__ __forceinline__ void attn_item(PP p, int layer, int b, int h, int qt, char* lds, const int tid_, unsigned* next_ctr, volatile XLAS unsigned* slot) {
;     ...
;     if (tid_ == 0) *slot = nxt_item;
.LBB0_421:
	s_cbranch_execz .Lslot_skip_a
	s_waitcnt vmcnt(8)
	ds_write_b32 v1, v250 offset:8
.Lslot_skip_a:
.LBB0_422:
	s_or_b64 exec, exec, s[8:9]
	s_waitcnt lgkmcnt(0)
	s_barrier
	s_mov_b64 s[8:9], 0

; template <int DQ, int TYPE>
; __device__ __forceinline__ void attn_item(PP p, int layer, int b, int h, int qt, char* lds, const int tid_, unsigned* next_ctr, volatile XLAS unsigned* slot) {
;     ...
;         if (j < j_hi) A_LSTORE(A, buf ^ 1);
;         __syncthreads();
;     }
;     ...
;     __builtin_amdgcn_s_setprio(0);
;     unsigned nxt_item = 0; if (tid_ == 0) nxt_item = atomicAdd(next_ctr, 1u);
;     l_run += __shfl_xor(l_run, 32);
;     float* mrg = (float*)lds;
;     {
;         float* mp = mrg + (size_t)((qg * 2 + kh) * 34) * 64 + lane;
;         if (kh == 0) {
; #pragma unroll
;             for (int t2 = 0; t2 < 2; ++t2)
; #pragma unroll
;                 for (int i = 0; i < 16; ++i) mp[(t2 * 16 + i) * 64] = O[2 + t2][i];
;         } else {
; #pragma unroll
;             for (int t2 = 0; t2 < 2; ++t2)
; #pragma unroll
;                 for (int i = 0; i < 16; ++i) mp[(t2 * 16 + i) * 64] = O[t2][i];
;         }
;         mp[32 * 64] = m_run; mp[33 * 64] = l_run;
;     }
;     __syncthreads();
.LBB0_648:
	s_add_i32 s61, s61, 1
	s_add_i32 s62, s62, 64
	s_cmp_eq_u32 s60, s61
	s_waitcnt lgkmcnt(0)
	s_barrier
	s_cbranch_scc0 .LBB0_638
	s_setprio 0
	v_mov_b32_e32 v74, 0
	v_cmp_eq_u32_e64 s[50:51], 0, v181
	s_and_saveexec_b64 s[12:13], s[50:51]
	s_cbranch_execz .LBB0_653
	s_mov_b64 s[16:17], exec
	v_mbcnt_lo_u32_b32 v66, s16, 0
	v_mbcnt_hi_u32_b32 v66, s17, v66
	v_cmp_eq_u32_e32 vcc, 0, v66
	s_and_saveexec_b64 s[14:15], vcc
	s_cbranch_execz .LBB0_652
	s_bcnt1_i32_b64 s16, s[16:17]
	s_lshl_b32 s17, s47, 2
	v_mov_b32_e32 v67, s17
	v_mov_b32_e32 v68, s16
	global_atomic_add v250, v67, v68, s[6:7] sc0
.LBB0_652:
	s_or_b64 exec, exec, s[14:15]
.LBB0_653:
	s_or_b64 exec, exec, s[12:13]
	s_load_dwordx2 s[14:15], s[0:1], 0x98
	s_lshl_b32 s12, s56, 12
	v_and_b32_e32 v67, 64, v224
	v_xor_b32_e32 v66, 32, v224
	v_add_u32_e32 v67, 64, v67
	s_waitcnt lgkmcnt(0)
	s_add_u32 s12, s14, s12
	s_addc_u32 s13, s15, 0
	s_lshl_b32 s14, s55, 1
	s_add_u32 s12, s12, s14
	v_cmp_lt_i32_e32 vcc, v66, v67
	s_addc_u32 s13, s13, 0
	s_lshl_b32 s14, s81, 1
	v_cndmask_b32_e32 v66, v224, v66, vcc
	s_add_i32 s15, s14, s54
	v_lshlrev_b32_e32 v66, 2, v66
	s_mulk_i32 s15, 0x2200
	ds_bpermute_b32 v66, v66, v164
	s_add_i32 s15, s15, 16
	v_lshlrev_b32_e32 v67, 2, v183
	v_add_u32_e32 v68, s15, v67
	s_xor_b32 s15, s54, 1
	s_add_i32 s14, s14, s15
	s_mulk_i32 s14, 0x2200
	v_cndmask_b32_e64 v76, v27, v59, s[52:53]
	s_waitcnt vmcnt(3)
	v_cndmask_b32_e64 v84, v19, v51, s[52:53]
	v_cndmask_b32_e64 v85, v18, v50, s[52:53]
	s_add_i32 s14, s14, 16
	s_waitcnt lgkmcnt(0)
	v_add_f32_e32 v66, v164, v66
	v_cndmask_b32_e64 v69, v33, v65, s[52:53]
	v_cndmask_b32_e64 v70, v32, v64, s[52:53]
	v_cndmask_b32_e64 v71, v31, v63, s[52:53]
	v_cndmask_b32_e64 v72, v30, v62, s[52:53]
	v_cndmask_b32_e64 v73, v29, v61, s[52:53]
	v_cndmask_b32_e64 v75, v28, v60, s[52:53]
	v_cndmask_b32_e64 v77, v26, v58, s[52:53]
	v_cndmask_b32_e64 v78, v25, v57, s[52:53]
	v_cndmask_b32_e64 v79, v24, v56, s[52:53]
	v_cndmask_b32_e64 v80, v23, v55, s[52:53]
	v_cndmask_b32_e64 v81, v22, v54, s[52:53]
	v_cndmask_b32_e64 v82, v21, v53, s[52:53]
	v_cndmask_b32_e64 v83, v20, v52, s[52:53]
	s_waitcnt vmcnt(2)
	v_cndmask_b32_e64 v86, v17, v49, s[52:53]
	v_cndmask_b32_e64 v87, v16, v48, s[52:53]
	v_cndmask_b32_e64 v88, v15, v47, s[52:53]
	v_cndmask_b32_e64 v89, v14, v46, s[52:53]
	v_cndmask_b32_e64 v90, v13, v45, s[52:53]
	v_cndmask_b32_e64 v91, v12, v44, s[52:53]
	v_cndmask_b32_e64 v92, v11, v43, s[52:53]
	v_cndmask_b32_e64 v93, v10, v42, s[52:53]
	v_cndmask_b32_e64 v94, v9, v41, s[52:53]
	v_cndmask_b32_e64 v95, v8, v40, s[52:53]
	v_cndmask_b32_e64 v96, v7, v39, s[52:53]
	v_cndmask_b32_e64 v97, v6, v38, s[52:53]
	v_cndmask_b32_e64 v98, v5, v37, s[52:53]
	v_cndmask_b32_e64 v99, v4, v36, s[52:53]
	v_cndmask_b32_e64 v100, v3, v35, s[52:53]
	v_cndmask_b32_e64 v101, v2, v34, s[52:53]
	ds_write2st64_b32 v68, v85, v84 offset1:1
	ds_write2st64_b32 v68, v83, v82 offset0:2 offset1:3
	ds_write2st64_b32 v68, v81, v80 offset0:4 offset1:5
	ds_write2st64_b32 v68, v79, v78 offset0:6 offset1:7
	ds_write2st64_b32 v68, v77, v76 offset0:8 offset1:9
	ds_write2st64_b32 v68, v75, v73 offset0:10 offset1:11
	ds_write2st64_b32 v68, v72, v71 offset0:12 offset1:13
	ds_write2st64_b32 v68, v70, v69 offset0:14 offset1:15
	ds_write2st64_b32 v68, v101, v100 offset0:16 offset1:17
	ds_write2st64_b32 v68, v99, v98 offset0:18 offset1:19
	ds_write2st64_b32 v68, v97, v96 offset0:20 offset1:21
	ds_write2st64_b32 v68, v95, v94 offset0:22 offset1:23
	ds_write2st64_b32 v68, v93, v92 offset0:24 offset1:25
	ds_write2st64_b32 v68, v91, v90 offset0:26 offset1:27
	ds_write2st64_b32 v68, v89, v88 offset0:28 offset1:29
	ds_write2st64_b32 v68, v87, v86 offset0:30 offset1:31
	ds_write2st64_b32 v68, v165, v66 offset0:32 offset1:33
	v_add_u32_e32 v76, s14, v67
	s_waitcnt lgkmcnt(0)
	s_barrier
	ds_read2st64_b32 v[68:69], v76 offset0:32 offset1:33
	v_max_f32_e32 v70, v165, v165
	s_waitcnt lgkmcnt(0)
	v_max_f32_e32 v67, v68, v68
	v_max_f32_e32 v67, v70, v67
	v_sub_f32_e32 v70, v165, v67
	v_sub_f32_e32 v67, v68, v67
	v_exp_f32_e32 v67, v67
	v_exp_f32_e32 v68, v70
	v_mul_f32_e32 v69, v69, v67
	v_fmac_f32_e32 v69, v66, v68
	v_div_scale_f32 v66, s[14:15], v69, v69, 1.0
	v_rcp_f32_e32 v70, v66
	s_nop 0
	v_fma_f32 v71, -v66, v70, 1.0
	v_fmac_f32_e32 v70, v71, v70
	v_div_scale_f32 v71, vcc, 1.0, v69, 1.0
	v_mul_f32_e32 v72, v71, v70
	v_fma_f32 v73, -v66, v72, v71
	v_fmac_f32_e32 v72, v73, v70
	v_fma_f32 v66, -v66, v72, v71
	v_div_fmas_f32 v66, v66, v70, v72
	v_lshlrev_b64 v[70:71], 12, v[0:1]
	v_lshl_add_u64 v[70:71], s[12:13], 0, v[70:71]
	s_mov_b64 s[12:13], 0x27388400
	v_div_fixup_f32 v75, v66, v69, 1.0
	v_lshl_add_u64 v[70:71], v[70:71], 0, s[12:13]
	s_mov_b64 s[12:13], -1
	s_andn2_b64 vcc, exec, s[8:9]
	v_lshlrev_b32_e32 v0, 1, v147
	s_cbranch_vccnz .LBB0_682
; __device__ __forceinline__ float fast_exp2(float x) { return __builtin_amdgcn_exp2f(x); }
; template <int DQ, int TYPE>
; __device__ __forceinline__ void attn_item(PP p, int layer, int b, int h, int qt, char* lds, const int tid_, unsigned* next_ctr, volatile XLAS unsigned* slot) {
;     ...
;     {
;         const float* mp = mrg + (size_t)((qg * 2 + (kh ^ 1)) * 34) * 64 + lane;
;         const float m1 = mp[32 * 64], l1 = mp[33 * 64];
;         const float mt = fmaxf(m_run, m1);
;         const float a0 = fast_exp2(m_run - mt), a1 = fast_exp2(m1 - mt);
;         const float inv = 1.0f / (l_run * a0 + l1 * a1);
;         bf16_t* orow = Op + (size_t)qpos * D;
;     ...
;         if (kh == 0) A_MERGE(0); else A_MERGE(2);
	ds_read2st64_b32 v[78:79], v76 offset1:1
	v_mov_b32_e32 v66, v50
	v_lshl_add_u64 v[72:73], v[70:71], 0, v[0:1]
	s_waitcnt lgkmcnt(0)
	v_mov_b32_e32 v69, v78
	v_pk_mul_f32 v[80:81], v[66:67], v[68:69]
	v_mov_b32_e32 v66, v51
	v_add_f32_e32 v50, v80, v81
	v_mov_b32_e32 v69, v79
	v_mul_f32_e32 v77, v75, v50
	v_pk_mul_f32 v[50:51], v[66:67], v[68:69]
	v_mov_b32_e32 v66, v52
	v_add_f32_e32 v50, v50, v51
	v_mul_f32_e32 v80, v75, v50
	ds_read2st64_b32 v[50:51], v76 offset0:2 offset1:3
	s_waitcnt lgkmcnt(0)
	v_mov_b32_e32 v69, v50
	v_pk_mul_f32 v[78:79], v[66:67], v[68:69]
	v_mov_b32_e32 v66, v53
	v_add_f32_e32 v50, v78, v79
	v_mov_b32_e32 v69, v51
	v_mul_f32_e32 v52, v75, v50
	v_pk_mul_f32 v[50:51], v[66:67], v[68:69]
	v_mov_b32_e32 v66, v54
	v_add_f32_e32 v50, v50, v51
	v_mul_f32_e32 v51, v75, v50
	v_cvt_pk_bf16_f32 v50, v77, v80
	v_cvt_pk_bf16_f32 v51, v52, v51
	global_store_dwordx2 v[72:73], v[50:51], off offset:128
	ds_read2st64_b32 v[50:51], v76 offset0:4 offset1:5
	s_waitcnt lgkmcnt(0)
	v_mov_b32_e32 v69, v50
	v_pk_mul_f32 v[52:53], v[66:67], v[68:69]
	v_mov_b32_e32 v66, v55
	v_add_f32_e32 v50, v52, v53
	v_mov_b32_e32 v69, v51
	v_mul_f32_e32 v54, v75, v50
	v_pk_mul_f32 v[50:51], v[66:67], v[68:69]
	v_mov_b32_e32 v66, v56
	v_add_f32_e32 v50, v50, v51
	v_mul_f32_e32 v55, v75, v50
	ds_read2st64_b32 v[50:51], v76 offset0:6 offset1:7
	s_waitcnt lgkmcnt(0)
	v_mov_b32_e32 v69, v50
	v_pk_mul_f32 v[52:53], v[66:67], v[68:69]
	v_mov_b32_e32 v66, v57
	v_add_f32_e32 v50, v52, v53
	v_mov_b32_e32 v69, v51
	v_mul_f32_e32 v52, v75, v50
	v_pk_mul_f32 v[50:51], v[66:67], v[68:69]
	v_mov_b32_e32 v66, v58
	v_add_f32_e32 v50, v50, v51
	v_mul_f32_e32 v51, v75, v50
	v_cvt_pk_bf16_f32 v50, v54, v55
	v_cvt_pk_bf16_f32 v51, v52, v51
	global_store_dwordx2 v[72:73], v[50:51], off offset:144
	ds_read2st64_b32 v[50:51], v76 offset0:8 offset1:9
	s_waitcnt lgkmcnt(0)
	v_mov_b32_e32 v69, v50
	v_pk_mul_f32 v[52:53], v[66:67], v[68:69]
	v_mov_b32_e32 v66, v59
	v_add_f32_e32 v50, v52, v53
	v_mov_b32_e32 v69, v51
	v_mul_f32_e32 v54, v75, v50
	v_pk_mul_f32 v[50:51], v[66:67], v[68:69]
	v_mov_b32_e32 v66, v60
	v_add_f32_e32 v50, v50, v51
	v_mul_f32_e32 v55, v75, v50
	ds_read2st64_b32 v[50:51], v76 offset0:10 offset1:11
	s_waitcnt lgkmcnt(0)
	v_mov_b32_e32 v69, v50
	v_pk_mul_f32 v[52:53], v[66:67], v[68:69]
	v_mov_b32_e32 v66, v61
	v_add_f32_e32 v50, v52, v53
	v_mov_b32_e32 v69, v51
	v_mul_f32_e32 v52, v75, v50
	v_pk_mul_f32 v[50:51], v[66:67], v[68:69]
	v_mov_b32_e32 v66, v62
	v_add_f32_e32 v50, v50, v51
	v_mul_f32_e32 v51, v75, v50
	v_cvt_pk_bf16_f32 v50, v54, v55
	v_cvt_pk_bf16_f32 v51, v52, v51
	global_store_dwordx2 v[72:73], v[50:51], off offset:160
	ds_read2st64_b32 v[50:51], v76 offset0:12 offset1:13
	s_waitcnt lgkmcnt(0)
	v_mov_b32_e32 v69, v50
	v_pk_mul_f32 v[52:53], v[66:67], v[68:69]
	v_mov_b32_e32 v66, v63
	v_add_f32_e32 v50, v52, v53
	v_mov_b32_e32 v69, v51
	v_mul_f32_e32 v54, v75, v50
	v_pk_mul_f32 v[50:51], v[66:67], v[68:69]
	v_mov_b32_e32 v66, v64
	v_add_f32_e32 v50, v50, v51
	v_mul_f32_e32 v55, v75, v50
	ds_read2st64_b32 v[50:51], v76 offset0:14 offset1:15
	s_waitcnt lgkmcnt(0)
	v_mov_b32_e32 v69, v50
	v_pk_mul_f32 v[52:53], v[66:67], v[68:69]
	v_mov_b32_e32 v66, v65
	v_add_f32_e32 v50, v52, v53
	v_mov_b32_e32 v69, v51
	v_mul_f32_e32 v52, v75, v50
	v_pk_mul_f32 v[50:51], v[66:67], v[68:69]
	v_mov_b32_e32 v66, v34
	v_add_f32_e32 v50, v50, v51
	v_mul_f32_e32 v51, v75, v50
	v_cvt_pk_bf16_f32 v50, v54, v55
	v_cvt_pk_bf16_f32 v51, v52, v51
	global_store_dwordx2 v[72:73], v[50:51], off offset:176
	ds_read2st64_b32 v[50:51], v76 offset0:16 offset1:17
	s_waitcnt lgkmcnt(0)
	v_mov_b32_e32 v69, v50
	v_pk_mul_f32 v[52:53], v[66:67], v[68:69]
	v_mov_b32_e32 v66, v35
	v_add_f32_e32 v34, v52, v53
	v_mov_b32_e32 v69, v51
	v_mul_f32_e32 v52, v75, v34
	v_pk_mul_f32 v[34:35], v[66:67], v[68:69]
	v_mov_b32_e32 v66, v36
	v_add_f32_e32 v34, v34, v35
	v_mul_f32_e32 v53, v75, v34
	ds_read2st64_b32 v[34:35], v76 offset0:18 offset1:19
	s_waitcnt lgkmcnt(0)
	v_mov_b32_e32 v69, v34
	v_pk_mul_f32 v[50:51], v[66:67], v[68:69]
	v_mov_b32_e32 v66, v37
	v_add_f32_e32 v34, v50, v51
	v_mov_b32_e32 v69, v35
	v_mul_f32_e32 v36, v75, v34
	v_pk_mul_f32 v[34:35], v[66:67], v[68:69]
	v_mov_b32_e32 v66, v38
	v_add_f32_e32 v34, v34, v35
	v_mul_f32_e32 v35, v75, v34
	v_cvt_pk_bf16_f32 v34, v52, v53
	v_cvt_pk_bf16_f32 v35, v36, v35
	global_store_dwordx2 v[72:73], v[34:35], off offset:192
	ds_read2st64_b32 v[34:35], v76 offset0:20 offset1:21
	s_waitcnt lgkmcnt(0)
	v_mov_b32_e32 v69, v34
	v_pk_mul_f32 v[36:37], v[66:67], v[68:69]
	v_mov_b32_e32 v66, v39
	v_add_f32_e32 v34, v36, v37
	v_mov_b32_e32 v69, v35
	v_mul_f32_e32 v38, v75, v34
	v_pk_mul_f32 v[34:35], v[66:67], v[68:69]
	v_mov_b32_e32 v66, v40
	v_add_f32_e32 v34, v34, v35
	v_mul_f32_e32 v39, v75, v34
	ds_read2st64_b32 v[34:35], v76 offset0:22 offset1:23
	s_waitcnt lgkmcnt(0)
	v_mov_b32_e32 v69, v34
	v_pk_mul_f32 v[36:37], v[66:67], v[68:69]
	v_mov_b32_e32 v66, v41
	v_add_f32_e32 v34, v36, v37
	v_mov_b32_e32 v69, v35
	v_mul_f32_e32 v36, v75, v34
	v_pk_mul_f32 v[34:35], v[66:67], v[68:69]
	v_mov_b32_e32 v66, v42
	v_add_f32_e32 v34, v34, v35
	v_mul_f32_e32 v35, v75, v34
	v_cvt_pk_bf16_f32 v34, v38, v39
	v_cvt_pk_bf16_f32 v35, v36, v35
	global_store_dwordx2 v[72:73], v[34:35], off offset:208
	ds_read2st64_b32 v[34:35], v76 offset0:24 offset1:25
	s_waitcnt lgkmcnt(0)
	v_mov_b32_e32 v69, v34
	v_pk_mul_f32 v[36:37], v[66:67], v[68:69]
	v_mov_b32_e32 v66, v43
	v_add_f32_e32 v34, v36, v37
	v_mov_b32_e32 v69, v35
	v_mul_f32_e32 v38, v75, v34
	v_pk_mul_f32 v[34:35], v[66:67], v[68:69]
	v_mov_b32_e32 v66, v44
	v_add_f32_e32 v34, v34, v35
	v_mul_f32_e32 v39, v75, v34
	ds_read2st64_b32 v[34:35], v76 offset0:26 offset1:27
	s_waitcnt lgkmcnt(0)
	v_mov_b32_e32 v69, v34
	v_pk_mul_f32 v[36:37], v[66:67], v[68:69]
	v_mov_b32_e32 v66, v45
	v_add_f32_e32 v34, v36, v37
	v_mov_b32_e32 v69, v35
	v_mul_f32_e32 v36, v75, v34
	v_pk_mul_f32 v[34:35], v[66:67], v[68:69]
	v_mov_b32_e32 v66, v46
	v_add_f32_e32 v34, v34, v35
	v_mul_f32_e32 v35, v75, v34
	v_cvt_pk_bf16_f32 v34, v38, v39
	v_cvt_pk_bf16_f32 v35, v36, v35
	global_store_dwordx2 v[72:73], v[34:35], off offset:224
	ds_read2st64_b32 v[34:35], v76 offset0:28 offset1:29
	s_waitcnt lgkmcnt(0)
	v_mov_b32_e32 v69, v34
	v_pk_mul_f32 v[36:37], v[66:67], v[68:69]
	v_mov_b32_e32 v66, v47
	v_add_f32_e32 v34, v36, v37
	v_mov_b32_e32 v69, v35
	v_mul_f32_e32 v38, v75, v34
	v_pk_mul_f32 v[34:35], v[66:67], v[68:69]
	v_mov_b32_e32 v66, v48
	v_add_f32_e32 v34, v34, v35
	v_mul_f32_e32 v39, v75, v34
	ds_read2st64_b32 v[34:35], v76 offset0:30 offset1:31
	s_waitcnt lgkmcnt(0)
	v_mov_b32_e32 v69, v34
	v_pk_mul_f32 v[36:37], v[66:67], v[68:69]
	v_mov_b32_e32 v66, v49
	v_add_f32_e32 v34, v36, v37
	v_mov_b32_e32 v69, v35
	v_mul_f32_e32 v36, v75, v34
	v_pk_mul_f32 v[34:35], v[66:67], v[68:69]
	s_nop 0
	v_add_f32_e32 v34, v34, v35
	v_mul_f32_e32 v35, v75, v34
	v_cvt_pk_bf16_f32 v34, v38, v39
	v_cvt_pk_bf16_f32 v35, v36, v35
	global_store_dwordx2 v[72:73], v[34:35], off offset:240
	s_cbranch_execz .LBB0_683

; template <int DQ, int TYPE>
; __device__ __forceinline__ void attn_item(PP p, int layer, int b, int h, int qt, char* lds, const int tid_, unsigned* next_ctr, volatile XLAS unsigned* slot) {
;     ...
;     if (tid_ == 0) *slot = nxt_item;
;     __syncthreads();
.Lslot_skip_b:
.LBB0_657:
	s_or_b64 exec, exec, s[8:9]
	s_mov_b64 s[8:9], 0
	s_waitcnt lgkmcnt(0)
	s_barrier

; template <int DQ, int TYPE>
; __device__ __forceinline__ void attn_item(PP p, int layer, int b, int h, int qt, char* lds, const int tid_, unsigned* next_ctr, volatile XLAS unsigned* slot) {
;     ...
;         if (j < j_hi) A_LSTORE(A, buf ^ 1);
;         __syncthreads();
;     }
;     ...
;     __builtin_amdgcn_s_setprio(0);
;     unsigned nxt_item = 0; if (tid_ == 0) nxt_item = atomicAdd(next_ctr, 1u);
;     l_run += __shfl_xor(l_run, 32);
;     float* mrg = (float*)lds;
;     {
;         float* mp = mrg + (size_t)((qg * 2 + kh) * 34) * 64 + lane;
;         if (kh == 0) {
; #pragma unroll
;             for (int t2 = 0; t2 < 2; ++t2)
; #pragma unroll
;                 for (int i = 0; i < 16; ++i) mp[(t2 * 16 + i) * 64] = O[2 + t2][i];
;         } else {
; #pragma unroll
;             for (int t2 = 0; t2 < 2; ++t2)
; #pragma unroll
;                 for (int i = 0; i < 16; ++i) mp[(t2 * 16 + i) * 64] = O[t2][i];
;         }
;         mp[32 * 64] = m_run; mp[33 * 64] = l_run;
;     }
;     __syncthreads();
.LBB0_672:
	s_add_i32 s51, s51, 1
	s_add_i32 s57, s57, 64
	s_cmp_eq_u32 s49, s51
	s_waitcnt lgkmcnt(0)
	s_barrier
	s_cbranch_scc0 .LBB0_662
	s_setprio 0
	v_mov_b32_e32 v74, 0
	v_cmp_eq_u32_e64 s[50:51], 0, v181
	s_and_saveexec_b64 s[12:13], s[50:51]
	s_cbranch_execz .LBB0_677
	s_mov_b64 s[16:17], exec
	v_mbcnt_lo_u32_b32 v0, s16, 0
	v_mbcnt_hi_u32_b32 v0, s17, v0
	v_cmp_eq_u32_e32 vcc, 0, v0
	s_and_saveexec_b64 s[14:15], vcc
	s_cbranch_execz .LBB0_676
	s_bcnt1_i32_b64 s16, s[16:17]
	s_lshl_b32 s17, s47, 2
	v_mov_b32_e32 v66, s17
	v_mov_b32_e32 v67, s16
	global_atomic_add v250, v66, v67, s[6:7] sc0
.LBB0_676:
	s_or_b64 exec, exec, s[14:15]
.LBB0_677:
	s_or_b64 exec, exec, s[12:13]
	s_lshl_b32 s12, s55, 12
	s_add_u32 s12, s38, s12
	v_and_b32_e32 v66, 64, v224
	s_addc_u32 s13, s39, 0
	s_lshl_b32 s14, s54, 8
	v_xor_b32_e32 v0, 32, v224
	v_add_u32_e32 v66, 64, v66
	s_add_u32 s12, s12, s14
	v_cmp_lt_i32_e32 vcc, v0, v66
	s_addc_u32 s13, s13, 0
	s_lshl_b32 s14, s48, 1
	v_cndmask_b32_e32 v0, v224, v0, vcc
	s_add_i32 s15, s14, s56
	v_lshlrev_b32_e32 v0, 2, v0
	s_mulk_i32 s15, 0x2200
	ds_bpermute_b32 v0, v0, v199
	s_add_i32 s15, s15, 16
	v_lshlrev_b32_e32 v66, 2, v183
	v_add_u32_e32 v67, s15, v66
	s_xor_b32 s15, s56, 1
	s_add_i32 s14, s14, s15
	s_mulk_i32 s14, 0x2200
	v_cndmask_b32_e64 v76, v26, v58, s[52:53]
	v_cndmask_b32_e64 v83, v19, v51, s[52:53]
	v_cndmask_b32_e64 v84, v18, v50, s[52:53]
	s_add_i32 s14, s14, 16
	s_waitcnt lgkmcnt(0)
	v_add_f32_e32 v0, v199, v0
	v_cndmask_b32_e64 v68, v33, v65, s[52:53]
	v_cndmask_b32_e64 v69, v32, v64, s[52:53]
	v_cndmask_b32_e64 v70, v31, v63, s[52:53]
	v_cndmask_b32_e64 v71, v30, v62, s[52:53]
	v_cndmask_b32_e64 v72, v29, v61, s[52:53]
	v_cndmask_b32_e64 v73, v28, v60, s[52:53]
	v_cndmask_b32_e64 v75, v27, v59, s[52:53]
	v_cndmask_b32_e64 v77, v25, v57, s[52:53]
	v_cndmask_b32_e64 v78, v24, v56, s[52:53]
	v_cndmask_b32_e64 v79, v23, v55, s[52:53]
	v_cndmask_b32_e64 v80, v22, v54, s[52:53]
	v_cndmask_b32_e64 v81, v21, v53, s[52:53]
	v_cndmask_b32_e64 v82, v20, v52, s[52:53]
	v_cndmask_b32_e64 v85, v17, v49, s[52:53]
	s_waitcnt vmcnt(4)
	v_cndmask_b32_e64 v86, v16, v48, s[52:53]
	v_cndmask_b32_e64 v87, v15, v47, s[52:53]
	v_cndmask_b32_e64 v88, v14, v46, s[52:53]
	v_cndmask_b32_e64 v89, v13, v45, s[52:53]
	s_waitcnt vmcnt(3)
	v_cndmask_b32_e64 v90, v12, v44, s[52:53]
	v_cndmask_b32_e64 v91, v11, v43, s[52:53]
	v_cndmask_b32_e64 v92, v10, v42, s[52:53]
	v_cndmask_b32_e64 v93, v9, v41, s[52:53]
	v_cndmask_b32_e64 v94, v8, v40, s[52:53]
	v_cndmask_b32_e64 v95, v7, v39, s[52:53]
	v_cndmask_b32_e64 v96, v6, v38, s[52:53]
	v_cndmask_b32_e64 v97, v5, v37, s[52:53]
	v_cndmask_b32_e64 v98, v4, v36, s[52:53]
	v_cndmask_b32_e64 v99, v3, v35, s[52:53]
	v_cndmask_b32_e64 v100, v2, v34, s[52:53]
	ds_write2st64_b32 v67, v84, v83 offset1:1
	ds_write2st64_b32 v67, v82, v81 offset0:2 offset1:3
	ds_write2st64_b32 v67, v80, v79 offset0:4 offset1:5
	ds_write2st64_b32 v67, v78, v77 offset0:6 offset1:7
	ds_write2st64_b32 v67, v76, v75 offset0:8 offset1:9
	ds_write2st64_b32 v67, v73, v72 offset0:10 offset1:11
	ds_write2st64_b32 v67, v71, v70 offset0:12 offset1:13
	ds_write2st64_b32 v67, v69, v68 offset0:14 offset1:15
	ds_write2st64_b32 v67, v100, v99 offset0:16 offset1:17
	ds_write2st64_b32 v67, v98, v97 offset0:18 offset1:19
	ds_write2st64_b32 v67, v96, v95 offset0:20 offset1:21
	ds_write2st64_b32 v67, v94, v93 offset0:22 offset1:23
	ds_write2st64_b32 v67, v92, v91 offset0:24 offset1:25
	ds_write2st64_b32 v67, v90, v89 offset0:26 offset1:27
	ds_write2st64_b32 v67, v88, v87 offset0:28 offset1:29
	ds_write2st64_b32 v67, v86, v85 offset0:30 offset1:31
	ds_write2st64_b32 v67, v200, v0 offset0:32 offset1:33
	v_add_u32_e32 v76, s14, v66
	s_waitcnt lgkmcnt(0)
	s_barrier
	ds_read2st64_b32 v[68:69], v76 offset0:32 offset1:33
	v_max_f32_e32 v67, v200, v200
	s_waitcnt lgkmcnt(0)
	v_max_f32_e32 v66, v68, v68
	v_max_f32_e32 v66, v67, v66
	v_sub_f32_e32 v70, v200, v66
	v_sub_f32_e32 v66, v68, v66
	v_exp_f32_e32 v67, v66
	v_exp_f32_e32 v68, v70
	v_mul_f32_e32 v66, v69, v67
	v_fmac_f32_e32 v66, v0, v68
	v_div_scale_f32 v0, s[14:15], v66, v66, 1.0
	v_rcp_f32_e32 v69, v0
	s_nop 0
	v_fma_f32 v70, -v0, v69, 1.0
	v_fmac_f32_e32 v69, v70, v69
	v_div_scale_f32 v70, vcc, 1.0, v66, 1.0
	v_mul_f32_e32 v71, v70, v69
	v_fma_f32 v72, -v0, v71, v70
	v_fmac_f32_e32 v71, v72, v69
	v_fma_f32 v0, -v0, v71, v70
	v_div_fmas_f32 v0, v0, v69, v71
	v_lshlrev_b64 v[70:71], 12, v[172:173]
	v_div_fixup_f32 v75, v0, v66, 1.0
	v_lshl_add_u64 v[70:71], s[12:13], 0, v[70:71]
	s_mov_b64 s[12:13], -1
	s_andn2_b64 vcc, exec, s[8:9]
	v_lshlrev_b32_e32 v0, 1, v187
	s_cbranch_vccnz .LBB0_684
; __device__ __forceinline__ float fast_exp2(float x) { return __builtin_amdgcn_exp2f(x); }
; template <int DQ, int TYPE>
; __device__ __forceinline__ void attn_item(PP p, int layer, int b, int h, int qt, char* lds, const int tid_, unsigned* next_ctr, volatile XLAS unsigned* slot) {
;     ...
;     {
;         const float* mp = mrg + (size_t)((qg * 2 + (kh ^ 1)) * 34) * 64 + lane;
;         const float m1 = mp[32 * 64], l1 = mp[33 * 64];
;         const float mt = fmaxf(m_run, m1);
;         const float a0 = fast_exp2(m_run - mt), a1 = fast_exp2(m1 - mt);
;         const float inv = 1.0f / (l_run * a0 + l1 * a1);
;         bf16_t* orow = Op + (size_t)qpos * D;
;     ...
;         if (kh == 0) A_MERGE(0); else A_MERGE(2);
	ds_read2st64_b32 v[78:79], v76 offset1:1
	v_mov_b32_e32 v66, v50
	v_lshl_add_u64 v[72:73], v[70:71], 0, v[0:1]
	s_waitcnt lgkmcnt(0)
	v_mov_b32_e32 v69, v78
	v_pk_mul_f32 v[80:81], v[66:67], v[68:69]
	v_mov_b32_e32 v66, v51
	v_add_f32_e32 v50, v80, v81
	v_mov_b32_e32 v69, v79
	v_mul_f32_e32 v77, v75, v50
	v_pk_mul_f32 v[50:51], v[66:67], v[68:69]
	v_mov_b32_e32 v66, v52
	v_add_f32_e32 v50, v50, v51
	v_mul_f32_e32 v80, v75, v50
	ds_read2st64_b32 v[50:51], v76 offset0:2 offset1:3
	s_waitcnt lgkmcnt(0)
	v_mov_b32_e32 v69, v50
	v_pk_mul_f32 v[78:79], v[66:67], v[68:69]
	v_mov_b32_e32 v66, v53
	v_add_f32_e32 v50, v78, v79
	v_mov_b32_e32 v69, v51
	v_mul_f32_e32 v52, v75, v50
	v_pk_mul_f32 v[50:51], v[66:67], v[68:69]
	v_mov_b32_e32 v66, v54
	v_add_f32_e32 v50, v50, v51
	v_mul_f32_e32 v51, v75, v50
	v_cvt_pk_bf16_f32 v50, v77, v80
	v_cvt_pk_bf16_f32 v51, v52, v51
	global_store_dwordx2 v[72:73], v[50:51], off offset:128
	ds_read2st64_b32 v[50:51], v76 offset0:4 offset1:5
	s_waitcnt lgkmcnt(0)
	v_mov_b32_e32 v69, v50
	v_pk_mul_f32 v[52:53], v[66:67], v[68:69]
	v_mov_b32_e32 v66, v55
	v_add_f32_e32 v50, v52, v53
	v_mov_b32_e32 v69, v51
	v_mul_f32_e32 v54, v75, v50
	v_pk_mul_f32 v[50:51], v[66:67], v[68:69]
	v_mov_b32_e32 v66, v56
	v_add_f32_e32 v50, v50, v51
	v_mul_f32_e32 v55, v75, v50
	ds_read2st64_b32 v[50:51], v76 offset0:6 offset1:7
	s_waitcnt lgkmcnt(0)
	v_mov_b32_e32 v69, v50
	v_pk_mul_f32 v[52:53], v[66:67], v[68:69]
	v_mov_b32_e32 v66, v57
	v_add_f32_e32 v50, v52, v53
	v_mov_b32_e32 v69, v51
	v_mul_f32_e32 v52, v75, v50
	v_pk_mul_f32 v[50:51], v[66:67], v[68:69]
	v_mov_b32_e32 v66, v58
	v_add_f32_e32 v50, v50, v51
	v_mul_f32_e32 v51, v75, v50
	v_cvt_pk_bf16_f32 v50, v54, v55
	v_cvt_pk_bf16_f32 v51, v52, v51
	global_store_dwordx2 v[72:73], v[50:51], off offset:144
	ds_read2st64_b32 v[50:51], v76 offset0:8 offset1:9
	s_waitcnt lgkmcnt(0)
	v_mov_b32_e32 v69, v50
	v_pk_mul_f32 v[52:53], v[66:67], v[68:69]
	v_mov_b32_e32 v66, v59
	v_add_f32_e32 v50, v52, v53
	v_mov_b32_e32 v69, v51
	v_mul_f32_e32 v54, v75, v50
	v_pk_mul_f32 v[50:51], v[66:67], v[68:69]
	v_mov_b32_e32 v66, v60
	v_add_f32_e32 v50, v50, v51
	v_mul_f32_e32 v55, v75, v50
	ds_read2st64_b32 v[50:51], v76 offset0:10 offset1:11
	s_waitcnt lgkmcnt(0)
	v_mov_b32_e32 v69, v50
	v_pk_mul_f32 v[52:53], v[66:67], v[68:69]
	v_mov_b32_e32 v66, v61
	v_add_f32_e32 v50, v52, v53
	v_mov_b32_e32 v69, v51
	v_mul_f32_e32 v52, v75, v50
	v_pk_mul_f32 v[50:51], v[66:67], v[68:69]
	v_mov_b32_e32 v66, v62
	v_add_f32_e32 v50, v50, v51
	v_mul_f32_e32 v51, v75, v50
	v_cvt_pk_bf16_f32 v50, v54, v55
	v_cvt_pk_bf16_f32 v51, v52, v51
	global_store_dwordx2 v[72:73], v[50:51], off offset:160
	ds_read2st64_b32 v[50:51], v76 offset0:12 offset1:13
	s_waitcnt lgkmcnt(0)
	v_mov_b32_e32 v69, v50
	v_pk_mul_f32 v[52:53], v[66:67], v[68:69]
	v_mov_b32_e32 v66, v63
	v_add_f32_e32 v50, v52, v53
	v_mov_b32_e32 v69, v51
	v_mul_f32_e32 v54, v75, v50
	v_pk_mul_f32 v[50:51], v[66:67], v[68:69]
	v_mov_b32_e32 v66, v64
	v_add_f32_e32 v50, v50, v51
	v_mul_f32_e32 v55, v75, v50
	ds_read2st64_b32 v[50:51], v76 offset0:14 offset1:15
	s_waitcnt lgkmcnt(0)
	v_mov_b32_e32 v69, v50
	v_pk_mul_f32 v[52:53], v[66:67], v[68:69]
	v_mov_b32_e32 v66, v65
	v_add_f32_e32 v50, v52, v53
	v_mov_b32_e32 v69, v51
	v_mul_f32_e32 v52, v75, v50
	v_pk_mul_f32 v[50:51], v[66:67], v[68:69]
	v_mov_b32_e32 v66, v34
	v_add_f32_e32 v50, v50, v51
	v_mul_f32_e32 v51, v75, v50
	v_cvt_pk_bf16_f32 v50, v54, v55
	v_cvt_pk_bf16_f32 v51, v52, v51
	global_store_dwordx2 v[72:73], v[50:51], off offset:176
	ds_read2st64_b32 v[50:51], v76 offset0:16 offset1:17
	s_waitcnt lgkmcnt(0)
	v_mov_b32_e32 v69, v50
	v_pk_mul_f32 v[52:53], v[66:67], v[68:69]
	v_mov_b32_e32 v66, v35
	v_add_f32_e32 v34, v52, v53
	v_mov_b32_e32 v69, v51
	v_mul_f32_e32 v52, v75, v34
	v_pk_mul_f32 v[34:35], v[66:67], v[68:69]
	v_mov_b32_e32 v66, v36
	v_add_f32_e32 v34, v34, v35
	v_mul_f32_e32 v53, v75, v34
	ds_read2st64_b32 v[34:35], v76 offset0:18 offset1:19
	s_waitcnt lgkmcnt(0)
	v_mov_b32_e32 v69, v34
	v_pk_mul_f32 v[50:51], v[66:67], v[68:69]
	v_mov_b32_e32 v66, v37
	v_add_f32_e32 v34, v50, v51
	v_mov_b32_e32 v69, v35
	v_mul_f32_e32 v36, v75, v34
	v_pk_mul_f32 v[34:35], v[66:67], v[68:69]
	v_mov_b32_e32 v66, v38
	v_add_f32_e32 v34, v34, v35
	v_mul_f32_e32 v35, v75, v34
	v_cvt_pk_bf16_f32 v34, v52, v53
	v_cvt_pk_bf16_f32 v35, v36, v35
	global_store_dwordx2 v[72:73], v[34:35], off offset:192
	ds_read2st64_b32 v[34:35], v76 offset0:20 offset1:21
	s_waitcnt lgkmcnt(0)
	v_mov_b32_e32 v69, v34
	v_pk_mul_f32 v[36:37], v[66:67], v[68:69]
	v_mov_b32_e32 v66, v39
	v_add_f32_e32 v34, v36, v37
	v_mov_b32_e32 v69, v35
	v_mul_f32_e32 v38, v75, v34
	v_pk_mul_f32 v[34:35], v[66:67], v[68:69]
	v_mov_b32_e32 v66, v40
	v_add_f32_e32 v34, v34, v35
	v_mul_f32_e32 v39, v75, v34
	ds_read2st64_b32 v[34:35], v76 offset0:22 offset1:23
	s_waitcnt lgkmcnt(0)
	v_mov_b32_e32 v69, v34
	v_pk_mul_f32 v[36:37], v[66:67], v[68:69]
	v_mov_b32_e32 v66, v41
	v_add_f32_e32 v34, v36, v37
	v_mov_b32_e32 v69, v35
	v_mul_f32_e32 v36, v75, v34
	v_pk_mul_f32 v[34:35], v[66:67], v[68:69]
	v_mov_b32_e32 v66, v42
	v_add_f32_e32 v34, v34, v35
	v_mul_f32_e32 v35, v75, v34
	v_cvt_pk_bf16_f32 v34, v38, v39
	v_cvt_pk_bf16_f32 v35, v36, v35
	global_store_dwordx2 v[72:73], v[34:35], off offset:208
	ds_read2st64_b32 v[34:35], v76 offset0:24 offset1:25
	s_waitcnt lgkmcnt(0)
	v_mov_b32_e32 v69, v34
	v_pk_mul_f32 v[36:37], v[66:67], v[68:69]
	v_mov_b32_e32 v66, v43
	v_add_f32_e32 v34, v36, v37
	v_mov_b32_e32 v69, v35
	v_mul_f32_e32 v38, v75, v34
	v_pk_mul_f32 v[34:35], v[66:67], v[68:69]
	v_mov_b32_e32 v66, v44
	v_add_f32_e32 v34, v34, v35
	v_mul_f32_e32 v39, v75, v34
	ds_read2st64_b32 v[34:35], v76 offset0:26 offset1:27
	s_waitcnt lgkmcnt(0)
	v_mov_b32_e32 v69, v34
	v_pk_mul_f32 v[36:37], v[66:67], v[68:69]
	v_mov_b32_e32 v66, v45
	v_add_f32_e32 v34, v36, v37
	v_mov_b32_e32 v69, v35
	v_mul_f32_e32 v36, v75, v34
	v_pk_mul_f32 v[34:35], v[66:67], v[68:69]
	v_mov_b32_e32 v66, v46
	v_add_f32_e32 v34, v34, v35
	v_mul_f32_e32 v35, v75, v34
	v_cvt_pk_bf16_f32 v34, v38, v39
	v_cvt_pk_bf16_f32 v35, v36, v35
	global_store_dwordx2 v[72:73], v[34:35], off offset:224
	ds_read2st64_b32 v[34:35], v76 offset0:28 offset1:29
	s_waitcnt lgkmcnt(0)
	v_mov_b32_e32 v69, v34
	v_pk_mul_f32 v[36:37], v[66:67], v[68:69]
	v_mov_b32_e32 v66, v47
	v_add_f32_e32 v34, v36, v37
	v_mov_b32_e32 v69, v35
	v_mul_f32_e32 v38, v75, v34
	v_pk_mul_f32 v[34:35], v[66:67], v[68:69]
	v_mov_b32_e32 v66, v48
	v_add_f32_e32 v34, v34, v35
	v_mul_f32_e32 v39, v75, v34
	ds_read2st64_b32 v[34:35], v76 offset0:30 offset1:31
	s_waitcnt lgkmcnt(0)
	v_mov_b32_e32 v69, v34
	v_pk_mul_f32 v[36:37], v[66:67], v[68:69]
	v_mov_b32_e32 v66, v49
	v_add_f32_e32 v34, v36, v37
	v_mov_b32_e32 v69, v35
	v_mul_f32_e32 v36, v75, v34
	v_pk_mul_f32 v[34:35], v[66:67], v[68:69]
	s_nop 0
	v_add_f32_e32 v34, v34, v35
	v_mul_f32_e32 v35, v75, v34
	v_cvt_pk_bf16_f32 v34, v38, v39
	v_cvt_pk_bf16_f32 v35, v36, v35
	global_store_dwordx2 v[72:73], v[34:35], off offset:240
	s_cbranch_execz .LBB0_685

; template <int DQ, int TYPE>
; __device__ __forceinline__ void attn_item(PP p, int layer, int b, int h, int qt, char* lds, const int tid_, unsigned* next_ctr, volatile XLAS unsigned* slot) {
;     ...
;     if (tid_ == 0) *slot = nxt_item;
;     __syncthreads();
.LBB0_686:
	s_waitcnt vmcnt(8)
	ds_write_b32 v1, v250 offset:8
	s_branch .LBB0_384
